# XCD-local grid barriers at the 9 seams whose producers/consumers share an XCD, guarded by a runtime census that every XCC hosts exactly one blockIdx%8 class (else full barrier)
# speedup vs baseline: 1.0273x; 1.0191x over previous
_Z6mk_fwd4Args:
	s_mov_b32 s98, 0
	s_load_dword s3, s[0:1], 0xa0
	s_load_dwordx8 s[88:95], s[0:1], 0x80
	v_and_b32_e32 v254, 0x3ff, v0
	s_add_u32 s6, s0, 0x98
	s_addc_u32 s7, s1, 0
	s_waitcnt lgkmcnt(0)
	v_writelane_b32 v255, s3, 0
	v_readfirstlane_b32 s3, v254
	v_cmp_gt_u32_e32 vcc, 2, v254
	s_nop 0
	v_writelane_b32 v255, s3, 1
	s_and_saveexec_b64 s[4:5], vcc
	v_lshl_add_u32 v1, v254, 2, 0
	v_add_u32_e32 v1, 0x23000, v1
	v_mov_b32_e32 v2, 0
	ds_write_b32 v1, v2
	s_or_b64 exec, exec, s[4:5]
	s_add_u32 s14, s90, 0x4000
	s_addc_u32 s15, s91, 0
	s_sub_i32 s3, s93, s92
	s_cmp_lt_i32 s3, 2
	s_mov_b32 s97, 0
	s_waitcnt lgkmcnt(0)
	s_barrier
	s_cbranch_scc1 .LBB0_7
	s_getreg_b32 s4, hwreg(HW_REG_XCC_ID, 0, 4)
	s_and_b32 s97, s4, 15
	v_cmp_eq_u32_e32 vcc, 0, v254
	s_and_saveexec_b64 s[4:5], vcc
	s_cbranch_execz .LBB0_6
	s_mov_b64 s[8:9], exec
	v_mbcnt_lo_u32_b32 v1, s8, 0
	v_mbcnt_hi_u32_b32 v1, s9, v1
	v_cmp_eq_u32_e32 vcc, 0, v1
	s_and_b64 s[10:11], exec, vcc
	s_mov_b64 exec, s[10:11]
	s_cbranch_execz .LBB0_6
	s_lshl_b32 s10, s97, 8
	s_bcnt1_i32_b64 s8, s[8:9]
	v_mov_b32_e32 v1, s10
	v_mov_b32_e32 v2, s8
	global_atomic_add v1, v2, s[14:15] offset:1024
	s_and_b32 s16, s2, 7
	s_lshl_b32 s16, s16, 3
	s_mov_b64 s[18:19], 1
	s_lshl_b64 s[18:19], s[18:19], s16
	s_lshl_b32 s16, s97, 3
	v_mov_b32_e32 v4, s18
	v_mov_b32_e32 v5, s19
	v_mov_b32_e32 v3, s16
	global_atomic_add_x2 v[6:7], v3, v[4:5], s[90:91] offset:256 sc0
	s_waitcnt vmcnt(0)

.LBB0_321:
	s_or_b64 exec, exec, s[0:1]
	s_waitcnt lgkmcnt(0)
	s_barrier
	s_mov_b64 s[0:1], exec
	s_mov_b64 exec, 0xffff
	v_lshlrev_b32_e32 v20, 3, v251
	global_load_dwordx2 v[22:23], v20, s[90:91] offset:256 sc1
	s_waitcnt vmcnt(0)
	v_or_b32_e32 v24, v22, v23
	v_and_b32_e32 v25, v22, v23
	v_add_u32_e32 v26, -1, v24
	v_and_b32_e32 v26, v26, v24
	v_and_b32_e32 v27, 0x20202020, v24
	v_xor_b32_e32 v27, v27, v24
	v_or3_b32 v25, v25, v26, v27
	v_cmp_eq_u32_e32 vcc, 0, v25
	v_cmp_ne_u32_e64 s[6:7], 0, v24
	s_nop 3
	s_mov_b64 exec, s[0:1]
	s_bcnt1_i32_b64 s14, s[6:7]
	s_cmp_eq_u32 vcc_lo, 0xffff
	s_cselect_b32 s15, 1, 0
	s_cmp_eq_u32 s14, 8
	s_cselect_b32 s14, 1, 0
	s_and_b32 s15, s15, s14
	s_cmp_eq_u32 s94, 0x100
	s_cselect_b32 s14, 1, 0
	s_and_b32 s98, s15, s14

.LBB0_376:
	s_andn2_saveexec_b64 s[6:7], s[6:7]
	s_cbranch_execz .LBB0_394
	s_cmp_eq_u32 s98, 1
	s_cbranch_scc1 .Lxloc_2
	s_mov_b64 s[6:7], exec
	buffer_wbl2 sc1
	s_waitcnt lgkmcnt(0)
	s_waitcnt vmcnt(0)
	v_mbcnt_lo_u32_b32 v1, s6, 0
	v_mbcnt_hi_u32_b32 v1, s7, v1
	v_cmp_eq_u32_e32 vcc, 0, v1
	s_and_saveexec_b64 s[10:11], vcc
	s_cbranch_execz .LBB0_379
	s_bcnt1_i32_b64 s3, s[6:7]
	v_mov_b32_e32 v2, 0x7000
	v_mov_b32_e32 v3, s3
	global_atomic_add v2, v2, v3, s[90:91] offset:1024 sc0

.Lxloc_2:
	v_mov_b32_e32 v0, 0x2000
	v_mov_b32_e32 v1, 1
	s_waitcnt vmcnt(0)
	buffer_inv sc1
	global_atomic_add v0, v1, s[4:5] offset:1024
	s_waitcnt vmcnt(0)

.LBB0_473:
	s_andn2_saveexec_b64 s[6:7], s[6:7]
	s_cbranch_execz .LBB0_491
	s_cmp_eq_u32 s98, 1
	s_cbranch_scc1 .Lxloc_3
	s_mov_b64 s[6:7], exec
	buffer_wbl2 sc1
	s_waitcnt lgkmcnt(0)
	s_waitcnt vmcnt(0)
	v_mbcnt_lo_u32_b32 v1, s6, 0
	v_mbcnt_hi_u32_b32 v1, s7, v1
	v_cmp_eq_u32_e32 vcc, 0, v1
	s_and_saveexec_b64 s[8:9], vcc
	s_cbranch_execz .LBB0_476
	s_bcnt1_i32_b64 s3, s[6:7]
	v_mov_b32_e32 v2, 0x7000
	v_mov_b32_e32 v3, s3
	global_atomic_add v2, v2, v3, s[90:91] offset:1024 sc0

.LBB0_1185:
	s_andn2_saveexec_b64 s[8:9], s[8:9]
	s_cbranch_execz .LBB0_1203
	s_cmp_eq_u32 s98, 1
	s_cbranch_scc1 .Lxloc_10
	s_mov_b64 s[8:9], exec
	buffer_wbl2 sc1
	s_waitcnt lgkmcnt(0)
	s_waitcnt vmcnt(0)
	v_mbcnt_lo_u32_b32 v1, s8, 0
	v_mbcnt_hi_u32_b32 v1, s9, v1
	v_cmp_eq_u32_e32 vcc, 0, v1
	s_and_saveexec_b64 s[10:11], vcc
	s_cbranch_execz .LBB0_1188
	s_bcnt1_i32_b64 s3, s[8:9]
	v_mov_b32_e32 v2, 0x7000
	v_mov_b32_e32 v3, s3
	global_atomic_add v2, v2, v3, s[90:91] offset:1024 sc0

	.amdhsa_kernel _Z6mk_fwd4Args
		.amdhsa_group_segment_fixed_size 0
		.amdhsa_private_segment_fixed_size 0
		.amdhsa_kernarg_size 408
		.amdhsa_user_sgpr_count 2
		.amdhsa_user_sgpr_dispatch_ptr 0
		.amdhsa_user_sgpr_queue_ptr 0
		.amdhsa_user_sgpr_kernarg_segment_ptr 1
		.amdhsa_user_sgpr_dispatch_id 0
		.amdhsa_user_sgpr_kernarg_preload_length 0
		.amdhsa_user_sgpr_kernarg_preload_offset 0
		.amdhsa_user_sgpr_private_segment_size 0
		.amdhsa_uses_dynamic_stack 0
		.amdhsa_enable_private_segment 0
		.amdhsa_system_sgpr_workgroup_id_x 1
		.amdhsa_system_sgpr_workgroup_id_y 0
		.amdhsa_system_sgpr_workgroup_id_z 0
		.amdhsa_system_sgpr_workgroup_info 0
		.amdhsa_system_vgpr_workitem_id 2
		.amdhsa_next_free_vgpr 256
		.amdhsa_next_free_sgpr 100
		.amdhsa_accum_offset 256
		.amdhsa_reserve_vcc 1
		.amdhsa_float_round_mode_32 0
		.amdhsa_float_round_mode_16_64 0
		.amdhsa_float_denorm_mode_32 3
		.amdhsa_float_denorm_mode_16_64 3
		.amdhsa_dx10_clamp 1
		.amdhsa_ieee_mode 1
		.amdhsa_fp16_overflow 0
		.amdhsa_tg_split 0
		.amdhsa_exception_fp_ieee_invalid_op 0
		.amdhsa_exception_fp_denorm_src 0
		.amdhsa_exception_fp_ieee_div_zero 0
		.amdhsa_exception_fp_ieee_overflow 0
		.amdhsa_exception_fp_ieee_underflow 0
		.amdhsa_exception_fp_ieee_inexact 0
		.amdhsa_exception_int_div_zero 0
	.end_amdhsa_kernel

amdhsa.kernels:
  - .agpr_count:     0
    .args:
      - .offset:         0
        .size:           152
        .value_kind:     by_value
      - .offset:         152
        .size:           4
        .value_kind:     hidden_block_count_x
      - .offset:         156
        .size:           4
        .value_kind:     hidden_block_count_y
      - .offset:         160
        .size:           4
        .value_kind:     hidden_block_count_z
      - .offset:         164
        .size:           2
        .value_kind:     hidden_group_size_x
      - .offset:         166
        .size:           2
        .value_kind:     hidden_group_size_y
      - .offset:         168
        .size:           2
        .value_kind:     hidden_group_size_z
      - .offset:         170
        .size:           2
        .value_kind:     hidden_remainder_x
      - .offset:         172
        .size:           2
        .value_kind:     hidden_remainder_y
      - .offset:         174
        .size:           2
        .value_kind:     hidden_remainder_z
      - .offset:         192
        .size:           8
        .value_kind:     hidden_global_offset_x
      - .offset:         200
        .size:           8
        .value_kind:     hidden_global_offset_y
      - .offset:         208
        .size:           8
        .value_kind:     hidden_global_offset_z
      - .offset:         216
        .size:           2
        .value_kind:     hidden_grid_dims
      - .offset:         240
        .size:           8
        .value_kind:     hidden_multigrid_sync_arg
      - .offset:         272
        .size:           4
        .value_kind:     hidden_dynamic_lds_size
    .group_segment_fixed_size: 0
    .kernarg_segment_align: 8
    .kernarg_segment_size: 408
    .language:       OpenCL C
    .language_version:
      - 2
      - 0
    .max_flat_workgroup_size: 512
    .name:           _Z6mk_fwd4Args
    .private_segment_fixed_size: 0
    .sgpr_count:     106
    .sgpr_spill_count: 27
    .symbol:         _Z6mk_fwd4Args.kd
    .uniform_work_group_size: 1
    .uses_dynamic_stack: false
    .vgpr_count:     256
    .vgpr_spill_count: 0
    .wavefront_size: 64
